# mlstmA+mixC gate chains: DPP wave scan/max + readlane instead of ds_bpermute round trips
# speedup vs baseline: 1.0021x; 1.0021x over previous
; DI void conv_unit(const u16* __restrict__ PM, const float* __restrict__ conv_w, const float* __restrict__ conv_b, int b, int sl0, int ch, float scale, float* a8) {
;   { const float4 b0 = *(const float4*)(conv_b + ch), b1 = *(const float4*)(conv_b + ch + 4); a8[0] = b0.x; a8[1] = b0.y; a8[2] = b0.z; a8[3] = b0.w; a8[4] = b1.x; a8[5] = b1.y; a8[6] = b1.z; a8[7] = b1.w; }
; #pragma unroll
;   for (int j = 0; j < 4; ++j) {
;     const int sl = sl0 - 3 + j;
;     if (sl >= 0) {
;       const uint4 raw = *(const uint4*)(PM + ((size_t)b * SEQ + sl) * 1024 + ch);
;       float x8[8]; unpack8(raw, x8);
;       const float4 w0 = *(const float4*)(conv_w + j * 1024 + ch), w1 = *(const float4*)(conv_w + j * 1024 + ch + 4);
;       a8[0] += w0.x * x8[0]; a8[1] += w0.y * x8[1]; a8[2] += w0.z * x8[2]; a8[3] += w0.w * x8[3];
;       a8[4] += w1.x * x8[4]; a8[5] += w1.y * x8[5]; a8[6] += w1.z * x8[6]; a8[7] += w1.w * x8[7];
;     }
;   }
; DI void mlstmA_item(const Params& p, char* lds, int item) {
;     ...
;   if (wave == 0) {
;     const size_t row = (size_t)b * SEQ + c * 64 + lane;
;     const float ig = G[row * 8 + hd] + p.in[7][hd], fg = G[row * 8 + 4 + hd] + p.in[8][hd];
.Lma_noissue:
	v_mov_b32_e32 v18, v222
	s_and_b32 s18, s10, 0x7f
	s_ashr_i32 s12, s10, 9
	s_nop 0
	v_cmp_lt_u32_e32 vcc, 63, v18
	s_and_saveexec_b64 s[0:1], vcc
	s_xor_b64 s[0:1], exec, s[0:1]
	s_lshl_b32 s8, s18, 6
	s_ashr_i32 s13, s12, 31
	s_or_saveexec_b64 s[14:15], s[0:1]
	s_bfe_u32 s27, s10, 0x20007
	v_and_b32_e32 v19, 63, v18
	s_ashr_i32 s11, s10, 31
	v_mov_b64_e32 v[10:11], s[12:13]
	v_mov_b64_e32 v[0:1], s[8:9]
	v_mov_b32_e32 v50, s8
	s_xor_b64 exec, exec, s[14:15]
	s_cbranch_execz .LBB0_330
	s_ashr_i32 s13, s12, 31
	s_lshl_b64 s[0:1], s[12:13], 13
	s_lshl_b32 s18, s18, 6
	v_or_b32_e32 v0, s0, v18
	v_or_b32_e32 v0, s18, v0
	v_mov_b32_e32 v1, s1
	v_lshlrev_b64 v[0:1], 5, v[0:1]
	v_lshl_add_u64 v[0:1], s[52:53], 0, v[0:1]
	s_lshl_b32 s8, s27, 2
	v_lshl_add_u64 v[2:3], v[0:1], 0, s[8:9]
	v_mov_b32_e32 v1, s8
	global_load_dword v0, v[2:3], off
	global_load_dword v4, v1, s[66:67]
	s_nop 0
	global_load_dword v2, v[2:3], off offset:16
	s_nop 0
	global_load_dword v1, v1, s[36:37]
	v_and_b32_e32 v70, 15, v222
	s_bfe_u32 s72, s10, 0x20007
	v_lshlrev_b32_e32 v70, 3, v70
	s_lshl_b32 s72, s72, 7
	v_add_u32_e32 v70, s72, v70
	v_lshlrev_b32_e32 v71, 2, v70
	v_add_u32_e32 v72, 0x1000, v71
	v_add_u32_e32 v73, 0x2000, v71
	v_add_u32_e32 v74, 0x3000, v71
	global_load_dwordx4 v[140:143], v71, s[62:63] offset:2048
	global_load_dwordx4 v[144:147], v71, s[62:63] offset:2064
	global_load_dwordx4 v[148:151], v72, s[62:63] offset:2048
	global_load_dwordx4 v[152:155], v72, s[62:63] offset:2064
	global_load_dwordx4 v[156:159], v73, s[62:63] offset:2048
	global_load_dwordx4 v[160:163], v73, s[62:63] offset:2064
	global_load_dwordx4 v[164:167], v74, s[62:63] offset:2048
	global_load_dwordx4 v[168:171], v74, s[62:63] offset:2064
	global_load_dwordx4 v[224:227], v71, s[64:65] offset:2048
	global_load_dwordx4 v[228:231], v71, s[64:65] offset:2064
	s_ashr_i32 s74, s10, 9
	s_ashr_i32 s75, s74, 31
	s_lshl_b64 s[74:75], s[74:75], 24
	s_add_u32 s74, s74, s4
	s_addc_u32 s75, s75, s5
	v_lshlrev_b32_e32 v76, 1, v70
	v_mov_b32_e32 v77, 0
	v_lshl_add_u64 v[78:79], s[74:75], 0, v[76:77]
	s_and_b32 s76, s10, 0x7f
	s_lshl_b32 s76, s76, 6
	v_lshrrev_b32_e32 v75, 4, v222
	s_movk_i32 s77, 0x800
	v_add_u32_e32 v184, s76, v75
	v_add_u32_e32 v185, -1, v184
	v_mov_b32_e32 v114, 0
	v_mov_b32_e32 v115, 0
	v_mov_b32_e32 v116, 0
	v_mov_b32_e32 v117, 0
	v_mov_b32_e32 v118, 0
	v_mov_b32_e32 v119, 0
	v_mov_b32_e32 v120, 0
	v_mov_b32_e32 v121, 0
	v_mov_b32_e32 v122, 0
	v_mov_b32_e32 v123, 0
	v_mov_b32_e32 v124, 0
	v_mov_b32_e32 v125, 0
	v_mad_i64_i32 v[186:187], s[88:89], v185, s77, v[78:79]
	v_cmp_lt_i32_e64 s[84:85], 2, v184
	s_and_saveexec_b64 s[86:87], s[84:85]
	global_load_dwordx4 v[114:117], v[186:187], off offset:-3072
	s_or_b64 exec, exec, s[86:87]
	v_cmp_lt_i32_e64 s[84:85], 1, v184
	s_and_saveexec_b64 s[86:87], s[84:85]
	global_load_dwordx4 v[118:121], v[186:187], off offset:-1024
	s_or_b64 exec, exec, s[86:87]
	v_cmp_lt_i32_e64 s[84:85], 0, v184
	s_and_saveexec_b64 s[86:87], s[84:85]
	global_load_dwordx4 v[122:125], v[186:187], off offset:1024
	s_or_b64 exec, exec, s[86:87]
	global_load_dwordx4 v[126:129], v[186:187], off offset:3072
	v_add_u32_e32 v184, 32, v184
	v_add_u32_e32 v185, -1, v184
	v_mov_b32_e32 v130, 0
	v_mov_b32_e32 v131, 0
	v_mov_b32_e32 v132, 0
	v_mov_b32_e32 v133, 0
	v_mov_b32_e32 v134, 0
	v_mov_b32_e32 v135, 0
	v_mov_b32_e32 v136, 0
	v_mov_b32_e32 v137, 0
	v_mov_b32_e32 v172, 0
	v_mov_b32_e32 v173, 0
	v_mov_b32_e32 v174, 0
	v_mov_b32_e32 v175, 0
	v_mad_i64_i32 v[186:187], s[88:89], v185, s77, v[78:79]
	v_cmp_lt_i32_e64 s[84:85], 2, v184
	s_and_saveexec_b64 s[86:87], s[84:85]
	global_load_dwordx4 v[130:133], v[186:187], off offset:-3072
	s_or_b64 exec, exec, s[86:87]
	v_cmp_lt_i32_e64 s[84:85], 1, v184
	s_and_saveexec_b64 s[86:87], s[84:85]
	global_load_dwordx4 v[134:137], v[186:187], off offset:-1024
	s_or_b64 exec, exec, s[86:87]
	v_cmp_lt_i32_e64 s[84:85], 0, v184
	s_and_saveexec_b64 s[86:87], s[84:85]
	global_load_dwordx4 v[172:175], v[186:187], off offset:1024
	s_or_b64 exec, exec, s[86:87]
	global_load_dwordx4 v[176:179], v[186:187], off offset:3072
	s_mov_b32 s0, 0xb2a5705f
	s_waitcnt vmcnt(20)
	v_add_f32_e32 v0, v0, v4
	s_waitcnt vmcnt(18)
; DI float wmax(float v) { for (int o = 32; o; o >>= 1) v = fmaxf(v, __shfl_xor(v, o)); return v; }
; DI float log_sigmoid(float f) { return fminf(f, 0.f) - log1pf(expf(-fabsf(f))); }
; DI float scan_sum(float v, int lane) { for (int o = 1; o < 64; o <<= 1) { float tv = __shfl_up(v, o); if (lane >= o) v += tv; } return v; }
; DI void mlstmA_item(const Params& p, char* lds, int item) {
;     ...
;     const float bc = scan_sum(log_sigmoid(fg), lane);
;     const float as = ig - bc;
;     const float gmax = wmax(as);
;     const float B = __shfl(bc, 63);
;     win[lane] = expf(as - gmax);
;     if (lane == 0) { CSC[0] = B; CSC[1] = B + gmax; }
	v_add_f32_e32 v1, v2, v1
	v_mul_f32_e64 v2, |v1|, s23
	v_fma_f32 v3, |v1|, s23, -v2
	v_rndne_f32_e32 v5, v2
	v_fma_f32 v3, |v1|, s0, v3
	v_sub_f32_e32 v2, v2, v5
	v_add_f32_e32 v2, v2, v3
	v_exp_f32_e32 v2, v2
	v_cvt_i32_f32_e32 v3, v5
	s_mov_b32 s0, 0x42ce8ed0
	v_cmp_ngt_f32_e64 vcc, |v1|, s0
	s_mov_b32 s0, 0xc2b17218
	v_ldexp_f32 v2, v2, v3
	v_cndmask_b32_e32 v2, 0, v2, vcc
	v_cmp_nlt_f32_e64 vcc, |v1|, s0
	v_min_f32_e32 v4, 0, v1
	s_mov_b32 s0, 0x3f2aaaab
	v_cndmask_b32_e32 v1, v33, v2, vcc
	v_add_f32_e32 v5, 1.0, v1
	v_add_f32_e32 v2, -1.0, v5
	v_sub_f32_e32 v3, v2, v5
	v_add_f32_e32 v3, 1.0, v3
	v_sub_f32_e32 v2, v1, v2
	v_add_f32_e32 v6, v2, v3
	v_frexp_mant_f32_e32 v2, v5
	v_cmp_gt_f32_e32 vcc, s0, v2
	v_cvt_f64_f32_e32 v[2:3], v5
	v_frexp_exp_i32_f64_e32 v2, v[2:3]
	v_subbrev_co_u32_e32 v2, vcc, 0, v2, vcc
	v_sub_u32_e32 v3, 0, v2
	v_ldexp_f32 v5, v5, v3
	v_ldexp_f32 v3, v6, v3
	v_add_f32_e32 v6, -1.0, v5
	v_add_f32_e32 v7, 1.0, v6
	v_sub_f32_e32 v7, v5, v7
	v_add_f32_e32 v7, v3, v7
	v_add_f32_e32 v8, v6, v7
	v_sub_f32_e32 v6, v6, v8
	v_add_f32_e32 v6, v7, v6
	v_add_f32_e32 v7, 1.0, v5
	v_add_f32_e32 v9, -1.0, v7
	v_sub_f32_e32 v5, v5, v9
	v_add_f32_e32 v3, v3, v5
	v_add_f32_e32 v5, v7, v3
	v_sub_f32_e32 v7, v7, v5
	v_add_f32_e32 v3, v3, v7
	v_rcp_f32_e32 v7, v5
	v_cvt_f32_i32_e32 v2, v2
	s_mov_b32 s0, 0x3f317218
	v_mul_f32_e32 v9, v8, v7
	v_mul_f32_e32 v10, v5, v9
	v_fma_f32 v11, v9, v5, -v10
	v_fmac_f32_e32 v11, v9, v3
	v_add_f32_e32 v12, v10, v11
	v_sub_f32_e32 v13, v8, v12
	v_sub_f32_e32 v8, v8, v13
	v_sub_f32_e32 v10, v12, v10
	v_sub_f32_e32 v8, v8, v12
	v_add_f32_e32 v6, v6, v8
	v_sub_f32_e32 v8, v10, v11
	v_add_f32_e32 v6, v8, v6
	v_add_f32_e32 v8, v13, v6
	v_mul_f32_e32 v10, v7, v8
	v_mul_f32_e32 v11, v5, v10
	v_fma_f32 v5, v10, v5, -v11
	v_fmac_f32_e32 v5, v10, v3
	v_sub_f32_e32 v3, v13, v8
	v_add_f32_e32 v3, v6, v3
	v_add_f32_e32 v6, v11, v5
	v_sub_f32_e32 v12, v8, v6
	v_sub_f32_e32 v8, v8, v12
	v_sub_f32_e32 v11, v6, v11
	v_sub_f32_e32 v6, v8, v6
	v_add_f32_e32 v3, v3, v6
	v_sub_f32_e32 v5, v11, v5
	v_add_f32_e32 v3, v5, v3
	v_add_f32_e32 v5, v9, v10
	v_add_f32_e32 v3, v12, v3
	v_sub_f32_e32 v6, v5, v9
	v_mul_f32_e32 v3, v7, v3
	v_sub_f32_e32 v6, v10, v6
	v_add_f32_e32 v3, v6, v3
	v_mul_f32_e32 v9, 0x3f317218, v2
	v_add_f32_e32 v6, v5, v3
	v_fma_f32 v10, v2, s0, -v9
	v_mul_f32_e32 v7, v6, v6
	v_fmac_f32_e32 v10, 0xb102e308, v2
	v_sub_f32_e32 v2, v6, v5
	v_fmamk_f32 v8, v7, 0x3e9b6dac, v32
	v_sub_f32_e32 v2, v3, v2
	v_add_f32_e32 v3, v9, v10
	v_fmaak_f32 v8, v7, v8, 0x3f2aaada
	v_sub_f32_e32 v5, v3, v9
	v_ldexp_f32 v9, v6, 1
	v_mul_f32_e32 v6, v6, v7
	v_mul_f32_e32 v6, v6, v8
	v_add_f32_e32 v7, v9, v6
	v_sub_f32_e32 v8, v7, v9
	v_ldexp_f32 v2, v2, 1
	v_sub_f32_e32 v6, v6, v8
	v_add_f32_e32 v2, v2, v6
	v_add_f32_e32 v6, v7, v2
	v_sub_f32_e32 v7, v6, v7
	v_sub_f32_e32 v2, v2, v7
	v_add_f32_e32 v7, v3, v6
	v_sub_f32_e32 v8, v7, v3
	v_sub_f32_e32 v9, v7, v8
	v_sub_f32_e32 v5, v10, v5
	v_sub_f32_e32 v3, v3, v9
	v_sub_f32_e32 v6, v6, v8
	v_add_f32_e32 v3, v6, v3
	v_add_f32_e32 v6, v5, v2
	v_sub_f32_e32 v8, v6, v5
	v_sub_f32_e32 v9, v6, v8
	v_sub_f32_e32 v5, v5, v9
	v_sub_f32_e32 v2, v2, v8
	v_add_f32_e32 v3, v6, v3
	v_add_f32_e32 v2, v2, v5
	v_add_f32_e32 v5, v7, v3
	v_sub_f32_e32 v6, v5, v7
	v_sub_f32_e32 v3, v3, v6
	v_add_f32_e32 v2, v2, v3
	s_mov_b32 s0, 0x7f800000
	v_add_f32_e32 v2, v5, v2
	v_cmp_neq_f32_e32 vcc, s0, v1
	s_mov_b32 s0, 0x33800000
	s_nop 0
	v_cndmask_b32_e32 v2, v33, v2, vcc
	v_cmp_lt_f32_e64 vcc, |v1|, s0
	s_nop 0
	v_cndmask_b32_e32 v1, v2, v1, vcc
	v_sub_f32_e32 v1, v4, v1
	s_nop 1
	v_add_f32_dpp v1, v1, v1 row_shr:1 row_mask:0xf bank_mask:0xf
	s_nop 1
	v_add_f32_dpp v1, v1, v1 row_shr:2 row_mask:0xf bank_mask:0xf
	s_nop 1
	v_add_f32_dpp v1, v1, v1 row_shr:4 row_mask:0xf bank_mask:0xf
	s_nop 1
	v_add_f32_dpp v1, v1, v1 row_shr:8 row_mask:0xf bank_mask:0xf
	s_nop 1
	v_add_f32_dpp v1, v1, v1 row_bcast:15 row_mask:0xa bank_mask:0xf
	s_nop 1
	v_add_f32_dpp v1, v1, v1 row_bcast:31 row_mask:0xc bank_mask:0xf
	v_sub_f32_e32 v3, v0, v1
	v_mov_b32_e32 v2, v1
	v_mov_b32_e32 v5, v3
	s_nop 1
	v_max_f32_dpp v5, v5, v5 row_shr:1 row_mask:0xf bank_mask:0xf
	s_nop 1
	v_max_f32_dpp v5, v5, v5 row_shr:2 row_mask:0xf bank_mask:0xf
	s_nop 1
	v_max_f32_dpp v5, v5, v5 row_shr:4 row_mask:0xf bank_mask:0xf
	s_nop 1
	v_max_f32_dpp v5, v5, v5 row_shr:8 row_mask:0xf bank_mask:0xf
	s_nop 1
	v_max_f32_dpp v5, v5, v5 row_bcast:15 row_mask:0xa bank_mask:0xf
	s_nop 1
	v_max_f32_dpp v5, v5, v5 row_bcast:31 row_mask:0xc bank_mask:0xf
	s_nop 0
	v_readlane_b32 s1, v5, 63
	v_readlane_b32 s30, v2, 63
	v_cmp_eq_u32_e32 vcc, 0, v19
	s_mov_b32 s0, 0x3fb8aa3b
	s_nop 0
	v_mov_b32_e32 v0, s30
	v_mov_b32_e32 v1, s1
	v_sub_f32_e32 v2, v3, v1
	v_mul_f32_e32 v3, 0x3fb8aa3b, v2
	v_fma_f32 v4, v2, s0, -v3
	v_rndne_f32_e32 v5, v3
	v_fmac_f32_e32 v4, 0x32a5705f, v2
	v_sub_f32_e32 v3, v3, v5
	v_add_f32_e32 v3, v3, v4
	v_exp_f32_e32 v3, v3
	v_cvt_i32_f32_e32 v4, v5
	s_mov_b32 s0, 0xc2ce8ed0
	v_cmp_ngt_f32_e64 s[0:1], s0, v2
	v_ldexp_f32 v3, v3, v4
	s_nop 0
	v_cndmask_b32_e64 v3, 0, v3, s[0:1]
	s_mov_b32 s0, 0x42b17218
	v_cmp_nlt_f32_e64 s[0:1], s0, v2
	s_nop 1
	v_cndmask_b32_e64 v2, v33, v3, s[0:1]
	v_lshl_add_u32 v3, v19, 2, 0
	ds_write_b32 v3, v2 offset:36864
	s_and_saveexec_b64 s[0:1], vcc
	s_cbranch_execz .LBB0_329
	s_lshl_b64 s[30:31], s[10:11], 4
	s_add_u32 s30, s21, s30
	s_addc_u32 s31, s22, s31
	s_waitcnt lgkmcnt(1)
	v_add_f32_e32 v1, v1, v0
	global_store_dwordx2 v17, v[0:1], s[30:31]

; DI void mlstmC_pair(const Params& p, char* lds_all, int pair) {
;     ...
;   for (int i = 0; i < 4; ++i) {
;     const int q = ltid + 256 * i, e = q >> 3, s8 = (q & 7) * 8;
;     *(uint4*)(VTs + e * 72 + s8) = *(const uint4*)(VTm + ((size_t)(bh * 128 + e)) * SEQ + c * 64 + s8);
;   }
.LBB0_580:
	v_lshlrev_b32_e32 v20, 7, v53
	v_lshlrev_b32_e32 v2, 1, v52
	v_lshl_add_u64 v[0:1], s[56:57], 0, v[20:21]
	v_and_b32_e32 v20, 0x70, v2
	v_lshrrev_b32_e32 v2, 3, v42
	s_movk_i32 s0, 0xff80
	v_and_or_b32 v6, v45, s0, v2
	v_ashrrev_i32_e32 v7, 31, v6
	v_lshl_add_u64 v[4:5], v[0:1], 0, v[20:21]
	v_lshlrev_b64 v[0:1], 14, v[6:7]
	v_lshl_add_u64 v[0:1], v[4:5], 0, v[0:1]
	v_mul_u32_u24_e32 v2, 0x90, v2
	v_add3_u32 v7, v51, v20, v2
	global_load_dwordx4 v[0:3], v[0:1], off
	v_lshlrev_b32_e32 v36, 6, v53
	v_and_b32_e32 v26, 63, v46
	v_cmp_gt_u32_e64 s[0:1], 64, v42
	v_lshlrev_b64 v[22:23], 13, v[16:17]
	v_mbcnt_hi_u32_b32 v27, -1, v203
	v_or_b32_e32 v184, 32, v6
	v_ashrrev_i32_e32 v185, 31, v184
	v_lshlrev_b64 v[184:185], 14, v[184:185]
	v_lshl_add_u64 v[184:185], v[4:5], 0, v[184:185]
	global_load_dwordx4 v[118:121], v[184:185], off
	v_or_b32_e32 v184, 64, v6
	v_ashrrev_i32_e32 v185, 31, v184
	v_lshlrev_b64 v[184:185], 14, v[184:185]
	v_lshl_add_u64 v[184:185], v[4:5], 0, v[184:185]
	global_load_dwordx4 v[122:125], v[184:185], off
	v_or_b32_e32 v184, 0x60, v6
	v_ashrrev_i32_e32 v185, 31, v184
	v_lshlrev_b64 v[184:185], 14, v[184:185]
	v_lshl_add_u64 v[184:185], v[4:5], 0, v[184:185]
	global_load_dwordx4 v[126:129], v[184:185], off
	s_waitcnt vmcnt(3)
	ds_write_b128 v7, v[0:3] offset:34816
	s_waitcnt vmcnt(2)
	ds_write_b128 v7, v[118:121] offset:39424
	s_waitcnt vmcnt(1)
	ds_write_b128 v7, v[122:125] offset:44032
	s_waitcnt vmcnt(0)
	ds_write_b128 v7, v[126:129] offset:48640
	s_and_saveexec_b64 s[6:7], s[0:1]
	s_cbranch_execz .LBB0_582
; DI float log_sigmoid(float f) { return fminf(f, 0.f) - log1pf(expf(-fabsf(f))); }
; DI float scan_sum(float v, int lane) { for (int o = 1; o < 64; o <<= 1) { float tv = __shfl_up(v, o); if (lane >= o) v += tv; } return v; }
; DI float scan_max(float v, int lane) { for (int o = 1; o < 64; o <<= 1) { float tv = __shfl_up(v, o); if (lane >= o) v = fmaxf(v, tv); } return v; }
; DI void mlstmC_pair(const Params& p, char* lds_all, int pair) {
;     ...
;   if (lwave == 0) {
;     const size_t row = (size_t)b * SEQ + c * 64 + lane;
;     const float ig = G[row * 8 + hd] + p.in[7][hd], fg = G[row * 8 + 4 + hd] + p.in[8][hd];
;     const float bc = scan_sum(log_sigmoid(fg), lane);
;     const float as = ig - bc;
;     const float gm = scan_max(as, lane);
;     const float mt = bc + fmaxf(mprev, gm);
;     a_s[lane] = as; c_t[lane] = bc - mt; wint[lane] = expf(bc + mprev - mt); emt[lane] = expf(-mt);
	v_or_b32_e32 v0, v22, v26
	v_or_b32_e32 v0, v0, v36
	v_mov_b32_e32 v1, v23
	v_lshlrev_b64 v[0:1], 5, v[0:1]
	v_lshl_add_u64 v[0:1], s[52:53], 0, v[0:1]
	v_lshlrev_b32_e32 v20, 2, v44
	v_lshl_add_u64 v[2:3], v[0:1], 0, v[20:21]
	global_load_dword v0, v[2:3], off
	global_load_dword v1, v20, s[66:67]
	s_mov_b32 s0, 0xb2a5705f
	s_waitcnt vmcnt(0)
	v_add_f32_e32 v0, v0, v1
	global_load_dword v1, v[2:3], off offset:16
	s_nop 0
	global_load_dword v2, v20, s[36:37]
	s_waitcnt vmcnt(0)
	v_add_f32_e32 v1, v1, v2
	v_mul_f32_e64 v2, |v1|, s19
	v_fma_f32 v3, |v1|, s19, -v2
	v_rndne_f32_e32 v5, v2
	v_fma_f32 v3, |v1|, s0, v3
	v_sub_f32_e32 v2, v2, v5
	v_add_f32_e32 v2, v2, v3
	v_exp_f32_e32 v2, v2
	v_cvt_i32_f32_e32 v3, v5
	v_cmp_ngt_f32_e64 s[0:1], |v1|, s20
	v_min_f32_e32 v4, 0, v1
	v_ldexp_f32 v2, v2, v3
	v_cndmask_b32_e64 v2, 0, v2, s[0:1]
	v_cmp_nlt_f32_e64 s[0:1], |v1|, s21
	s_nop 1
	v_cndmask_b32_e64 v1, v50, v2, s[0:1]
	v_add_f32_e32 v5, 1.0, v1
	v_add_f32_e32 v2, -1.0, v5
	v_sub_f32_e32 v3, v2, v5
	v_add_f32_e32 v3, 1.0, v3
	v_sub_f32_e32 v2, v1, v2
	v_add_f32_e32 v6, v2, v3
	v_frexp_mant_f32_e32 v2, v5
	s_mov_b32 s0, 0x3f2aaaab
	v_cmp_gt_f32_e64 s[0:1], s0, v2
	v_cvt_f64_f32_e32 v[2:3], v5
	v_frexp_exp_i32_f64_e32 v2, v[2:3]
	v_subbrev_co_u32_e64 v2, s[0:1], 0, v2, s[0:1]
	v_sub_u32_e32 v3, 0, v2
	v_ldexp_f32 v5, v5, v3
	v_ldexp_f32 v3, v6, v3
	v_add_f32_e32 v6, -1.0, v5
	v_add_f32_e32 v7, 1.0, v6
	v_sub_f32_e32 v7, v5, v7
	v_add_f32_e32 v7, v3, v7
	v_add_f32_e32 v8, v6, v7
	v_sub_f32_e32 v6, v6, v8
	v_add_f32_e32 v6, v7, v6
	v_add_f32_e32 v7, 1.0, v5
	v_add_f32_e32 v9, -1.0, v7
	v_sub_f32_e32 v5, v5, v9
	v_add_f32_e32 v3, v3, v5
	v_add_f32_e32 v5, v7, v3
	v_sub_f32_e32 v7, v7, v5
	v_add_f32_e32 v3, v3, v7
	v_rcp_f32_e32 v7, v5
	v_cvt_f32_i32_e32 v2, v2
	s_mov_b32 s0, 0x3f317218
	v_mul_f32_e32 v9, v8, v7
	v_mul_f32_e32 v10, v5, v9
	v_fma_f32 v11, v9, v5, -v10
	v_fmac_f32_e32 v11, v9, v3
	v_add_f32_e32 v12, v10, v11
	v_sub_f32_e32 v13, v8, v12
	v_sub_f32_e32 v8, v8, v13
	v_sub_f32_e32 v10, v12, v10
	v_sub_f32_e32 v8, v8, v12
	v_add_f32_e32 v6, v6, v8
	v_sub_f32_e32 v8, v10, v11
	v_add_f32_e32 v6, v8, v6
	v_add_f32_e32 v8, v13, v6
	v_mul_f32_e32 v10, v7, v8
	v_mul_f32_e32 v11, v5, v10
	v_fma_f32 v5, v10, v5, -v11
	v_fmac_f32_e32 v5, v10, v3
	v_sub_f32_e32 v3, v13, v8
	v_add_f32_e32 v3, v6, v3
	v_add_f32_e32 v6, v11, v5
	v_sub_f32_e32 v12, v8, v6
	v_sub_f32_e32 v8, v8, v12
	v_sub_f32_e32 v11, v6, v11
	v_sub_f32_e32 v6, v8, v6
	v_add_f32_e32 v3, v3, v6
	v_sub_f32_e32 v5, v11, v5
	v_add_f32_e32 v3, v5, v3
	v_add_f32_e32 v5, v9, v10
	v_add_f32_e32 v3, v12, v3
	v_sub_f32_e32 v6, v5, v9
	v_mul_f32_e32 v3, v7, v3
	v_sub_f32_e32 v6, v10, v6
	v_add_f32_e32 v3, v6, v3
	v_mul_f32_e32 v9, 0x3f317218, v2
	v_add_f32_e32 v6, v5, v3
	v_fma_f32 v10, v2, s0, -v9
	v_mul_f32_e32 v7, v6, v6
	v_fmac_f32_e32 v10, 0xb102e308, v2
	v_sub_f32_e32 v2, v6, v5
	v_fmamk_f32 v8, v7, 0x3e9b6dac, v49
	v_sub_f32_e32 v2, v3, v2
	v_add_f32_e32 v3, v9, v10
	v_fmaak_f32 v8, v7, v8, 0x3f2aaada
	v_sub_f32_e32 v5, v3, v9
	v_ldexp_f32 v9, v6, 1
	v_mul_f32_e32 v6, v6, v7
	v_mul_f32_e32 v6, v6, v8
	v_add_f32_e32 v7, v9, v6
	v_sub_f32_e32 v8, v7, v9
	v_ldexp_f32 v2, v2, 1
	v_sub_f32_e32 v6, v6, v8
	v_add_f32_e32 v2, v2, v6
	v_add_f32_e32 v6, v7, v2
	v_sub_f32_e32 v7, v6, v7
	v_sub_f32_e32 v2, v2, v7
	v_add_f32_e32 v7, v3, v6
	v_sub_f32_e32 v8, v7, v3
	v_sub_f32_e32 v9, v7, v8
	v_sub_f32_e32 v5, v10, v5
	v_sub_f32_e32 v3, v3, v9
	v_sub_f32_e32 v6, v6, v8
	v_add_f32_e32 v3, v6, v3
	v_add_f32_e32 v6, v5, v2
	v_sub_f32_e32 v8, v6, v5
	v_sub_f32_e32 v9, v6, v8
	v_sub_f32_e32 v5, v5, v9
	v_sub_f32_e32 v2, v2, v8
	v_add_f32_e32 v3, v6, v3
	v_add_f32_e32 v2, v2, v5
	v_add_f32_e32 v5, v7, v3
	v_sub_f32_e32 v6, v5, v7
	v_sub_f32_e32 v3, v3, v6
	v_add_f32_e32 v2, v2, v3
	s_mov_b32 s0, 0x7f800000
	v_add_f32_e32 v2, v5, v2
	v_cmp_neq_f32_e64 s[0:1], s0, v1
	s_nop 1
	v_cndmask_b32_e64 v2, v50, v2, s[0:1]
	s_mov_b32 s0, 0x33800000
	v_cmp_lt_f32_e64 s[0:1], |v1|, s0
	s_nop 1
	v_cndmask_b32_e64 v1, v2, v1, s[0:1]
	v_sub_f32_e32 v3, v4, v1
	s_nop 1
	v_add_f32_dpp v3, v3, v3 row_shr:1 row_mask:0xf bank_mask:0xf
	s_nop 1
	v_add_f32_dpp v3, v3, v3 row_shr:2 row_mask:0xf bank_mask:0xf
	s_nop 1
	v_add_f32_dpp v3, v3, v3 row_shr:4 row_mask:0xf bank_mask:0xf
	s_nop 1
	v_add_f32_dpp v3, v3, v3 row_shr:8 row_mask:0xf bank_mask:0xf
	s_nop 1
	v_add_f32_dpp v3, v3, v3 row_bcast:15 row_mask:0xa bank_mask:0xf
	s_nop 1
	v_add_f32_dpp v3, v3, v3 row_bcast:31 row_mask:0xc bank_mask:0xf
	v_sub_f32_e32 v0, v0, v3
	v_mov_b32_e32 v1, v0
	s_nop 1
	v_max_f32_dpp v1, v1, v1 row_shr:1 row_mask:0xf bank_mask:0xf
	s_nop 1
	v_max_f32_dpp v1, v1, v1 row_shr:2 row_mask:0xf bank_mask:0xf
	s_nop 1
	v_max_f32_dpp v1, v1, v1 row_shr:4 row_mask:0xf bank_mask:0xf
	s_nop 1
	v_max_f32_dpp v1, v1, v1 row_shr:8 row_mask:0xf bank_mask:0xf
	s_nop 1
	v_max_f32_dpp v1, v1, v1 row_bcast:15 row_mask:0xa bank_mask:0xf
	s_nop 1
	v_max_f32_dpp v1, v1, v1 row_bcast:31 row_mask:0xc bank_mask:0xf
	s_mov_b32 s0, 0x3fb8aa3b
	v_max_f32_e32 v1, v1, v1
	v_max_f32_e32 v2, v43, v43
	v_max_f32_e32 v1, v2, v1
	v_add_f32_e32 v1, v3, v1
	v_lshl_add_u32 v2, v26, 2, v51
	v_sub_f32_e32 v4, v3, v1
	ds_write2st64_b32 v2, v0, v4 offset0:244 offset1:245
	v_add_f32_e32 v0, v43, v3
	v_sub_f32_e32 v0, v0, v1
	v_mul_f32_e32 v3, 0x3fb8aa3b, v0
	v_fma_f32 v4, v0, s0, -v3
	v_rndne_f32_e32 v5, v3
	v_fmac_f32_e32 v4, 0x32a5705f, v0
	v_sub_f32_e32 v3, v3, v5
	v_add_f32_e32 v3, v3, v4
	v_exp_f32_e32 v3, v3
	v_cvt_i32_f32_e32 v4, v5
	s_mov_b32 s0, 0xc2ce8ed0
	v_cmp_ngt_f32_e64 s[0:1], s0, v0
	v_ldexp_f32 v3, v3, v4
	s_nop 0
	v_cndmask_b32_e64 v3, 0, v3, s[0:1]
	s_mov_b32 s0, 0x42b17218
	v_cmp_nlt_f32_e64 s[0:1], s0, v0
	s_nop 1
	v_cndmask_b32_e64 v0, v50, v3, s[0:1]
	v_mul_f32_e32 v3, 0xbfb8aa3b, v1
	v_fma_f32 v4, v1, s19, -v3
	v_rndne_f32_e32 v5, v3
	v_fmac_f32_e32 v4, 0xb2a5705f, v1
	v_sub_f32_e32 v3, v3, v5
	v_add_f32_e32 v3, v3, v4
	v_exp_f32_e32 v3, v3
	v_cvt_i32_f32_e32 v4, v5
	v_cmp_nlt_f32_e64 s[0:1], s20, v1
	v_ldexp_f32 v3, v3, v4
	s_nop 0
	v_cndmask_b32_e64 v3, 0, v3, s[0:1]
	v_cmp_ngt_f32_e64 s[0:1], s21, v1
	s_nop 1
	v_cndmask_b32_e64 v1, v50, v3, s[0:1]
	ds_write2st64_b32 v2, v0, v1 offset0:246 offset1:247
